# sample-mLSTM unit: all 32 state-row loads requested at the very top of the unit (ahead of the q/k/v, n0 and gate phases), copied at their original sites; gate-load waits recounted
# speedup vs baseline: 1.0053x; 1.0038x over previous
; #define LAS __attribute__((address_space(3)))
; DI void smlstm_unit(const Args& a, LAS unsigned char* lds, int s, int h) {
;     ...
;     const int tid = threadIdx.x, lane = tid & 63, dv = tid & 127, part = tid >> 7;
;     const size_t row = (size_t)MPR + s; const int sh = s * 4 + h;
;     LAS float* QF = (LAS float*)lds; LAS float* KF = QF + 128; LAS float* VF = QF + 256; LAS float* RED = QF + 384; LAS float* HV = QF + 896; LAS float* SCL = QF + 1024;
;     const float* C0 = INF(a, I_SC) + (size_t)sh * 16384; const float* n0 = INF(a, I_SN) + sh * 128;
;     __syncthreads();
;     if (tid < 128) { QF[tid] = bf2f(((const bf16_t*)(ws + WS_QB))[row * 512 + h * 128 + tid]); KF[tid] = bf2f(((const bf16_t*)(ws + WS_KB))[row * 512 + h * 128 + tid]); VF[tid] = bf2f(((const bf16_t*)(ws + WS_VB))[row * 512 + h * 128 + tid]); }
;     ...
;       for (int i = 0; i < 32; ++i) c0v[i] = C0[(size_t)(part * 32 + i) * 128 + dv];
.LBB0_2126:
	s_add_i32 s0, s20, 0xfffffca0
	s_ashr_i32 s8, s0, 31
	s_lshr_b32 s8, s8, 25
	s_add_i32 s8, s0, s8
	s_and_b32 s8, s8, 0xffffff80
	s_sub_i32 s8, s0, s8
	s_ashr_i32 s0, s8, 2
	s_and_b32 s41, s8, 3
	s_addk_i32 s0, 0x4000
	s_ashr_i32 s101, s8, 31
	s_mov_b32 s100, s8
	s_lshl_b64 s[100:101], s[100:101], 16
	s_nop 0
	v_lshl_add_u64 v[214:215], v[134:135], 0, s[100:101]
	s_mov_b32 s101, 0
	s_mov_b32 s100, s38
	s_nop 0
	v_lshl_add_u64 v[216:217], v[214:215], 0, s[100:101]
	s_mov_b32 s100, s37
	s_nop 0
	v_lshl_add_u64 v[186:187], v[214:215], 0, s[100:101]
	s_mov_b32 s100, s22
	s_nop 0
	v_lshl_add_u64 v[188:189], v[214:215], 0, s[100:101]
	global_load_dword v219, v[214:215], off
	global_load_dword v220, v[214:215], off offset:512
	global_load_dword v221, v[214:215], off offset:1024
	global_load_dword v222, v[214:215], off offset:1536
	global_load_dword v223, v[214:215], off offset:2048
	global_load_dword v224, v[214:215], off offset:2560
	global_load_dword v225, v[214:215], off offset:3072
	global_load_dword v226, v[214:215], off offset:3584
	global_load_dword v227, v[216:217], off offset:-4096
	global_load_dword v190, v[186:187], off offset:512
	global_load_dword v191, v[186:187], off offset:1024
	global_load_dword v192, v[186:187], off offset:1536
	global_load_dword v193, v[216:217], off
	global_load_dword v194, v[216:217], off offset:512
	global_load_dword v195, v[216:217], off offset:1024
	global_load_dword v196, v[216:217], off offset:1536
	global_load_dword v197, v[216:217], off offset:2048
	global_load_dword v198, v[216:217], off offset:2560
	global_load_dword v199, v[216:217], off offset:3072
	global_load_dword v200, v[216:217], off offset:3584
	global_load_dword v201, v[186:187], off offset:2048
	global_load_dword v202, v[186:187], off offset:2560
	global_load_dword v203, v[186:187], off offset:3072
	global_load_dword v204, v[186:187], off offset:3584
	global_load_dword v205, v[188:189], off
	global_load_dword v206, v[188:189], off offset:512
	global_load_dword v207, v[188:189], off offset:1024
	global_load_dword v208, v[188:189], off offset:1536
	global_load_dword v209, v[188:189], off offset:2048
	global_load_dword v210, v[188:189], off offset:2560
	global_load_dword v211, v[188:189], off offset:3072
	global_load_dword v212, v[188:189], off offset:3584
	s_barrier
	s_and_saveexec_b64 s[16:17], s[2:3]
	s_cbranch_execz .LBB0_2128
	s_lshl_b64 s[18:19], s[0:1], 9
	s_lshl_b32 s9, s41, 7
	s_or_b32 s9, s18, s9
	v_mov_b32_e32 v3, s19
	v_or_b32_e32 v2, s9, v0
	v_lshlrev_b64 v[2:3], 1, v[2:3]
	v_lshl_add_u64 v[4:5], s[10:11], 0, v[2:3]
	v_lshl_add_u64 v[6:7], s[12:13], 0, v[2:3]
	v_lshl_add_u64 v[2:3], s[14:15], 0, v[2:3]
	global_load_ushort v4, v[4:5], off
	s_nop 0
	global_load_ushort v5, v[6:7], off
	s_nop 0
	global_load_ushort v2, v[2:3], off
	s_waitcnt vmcnt(2)
	v_lshlrev_b32_e32 v3, 16, v4
	s_waitcnt vmcnt(1)
	v_lshlrev_b32_e32 v4, 16, v5
	s_waitcnt vmcnt(0)
	v_lshlrev_b32_e32 v2, 16, v2
	ds_write2st64_b32 v218, v3, v4 offset1:2
	ds_write_b32 v218, v2 offset:1024

; DI void smlstm_unit(const Args& a, LAS unsigned char* lds, int s, int h) {
;     ...
;     const float* gr = (const float*)(ws + WS_GA) + row * 32; const float ip = gr[24 + h], fp = gr[28 + h], m0 = INF(a, I_SM)[sh];
;     const float lf = fminf(fp, 0.f) - log1pf(__expf(-fabsf(fp))), ain = lf + m0, mt = fmaxf(ain, ip), w_in = __expf(ain - mt), wi = __expf(ip - mt);
;     ...
;       for (int i = 0; i < 32; ++i) c0v[i] = C0[(size_t)(part * 32 + i) * 128 + dv];
.LBB0_2131:
	s_or_b64 exec, exec, s[20:21]
	s_ashr_i32 s9, s8, 31
	s_lshl_b64 s[20:21], s[0:1], 7
	s_add_u32 s20, s23, s20
	s_addc_u32 s21, s24, s21
	s_lshl_b32 s42, s41, 2
	v_mov_b32_e32 v2, s42
	global_load_dword v6, v2, s[20:21] offset:112
	global_load_dword v8, v2, s[20:21] offset:96
	s_lshl_b64 s[20:21], s[8:9], 2
	v_readlane_b32 s44, v253, 36
	v_readlane_b32 s45, v253, 37
	s_add_u32 s20, s44, s20
	s_addc_u32 s21, s45, s21
	global_load_dword v9, v133, s[20:21]
	s_lshl_b64 s[42:43], s[8:9], 16
	v_lshl_add_u64 v[2:3], v[134:135], 0, s[42:43]
	s_waitcnt lgkmcnt(1)
	v_add_co_u32_e32 v4, vcc, s38, v2
	s_waitcnt lgkmcnt(0)
	s_nop 0
	v_addc_co_u32_e32 v5, vcc, 0, v3, vcc
	s_barrier
	s_waitcnt vmcnt(3)
	v_mov_b32_e32 v19, v219
	v_mov_b32_e32 v32, v220
	v_mov_b32_e32 v33, v221
	v_mov_b32_e32 v34, v222
	v_mov_b32_e32 v44, v223
	v_mov_b32_e32 v45, v224
	v_mov_b32_e32 v46, v225
	v_mov_b32_e32 v47, v226
	v_mov_b32_e32 v48, v227
	s_add_u32 s20, s25, s42
	s_addc_u32 s21, s26, s43
	v_readlane_b32 s46, v253, 38
	v_readlane_b32 s47, v253, 39
	v_readlane_b32 s48, v253, 40
	v_readlane_b32 s49, v253, 41
	v_readlane_b32 s50, v253, 42
	v_readlane_b32 s51, v253, 43
	v_readlane_b32 s52, v253, 44
	v_readlane_b32 s53, v253, 45
	v_readlane_b32 s54, v253, 46
	v_readlane_b32 s55, v253, 47
	v_readlane_b32 s56, v253, 48
	v_readlane_b32 s57, v253, 49
	v_readlane_b32 s58, v253, 50
	v_readlane_b32 s59, v253, 51
	s_waitcnt vmcnt(2)
	v_mul_f32_e64 v7, |v6|, s31
	v_exp_f32_e32 v10, v7
	v_max_f32_e32 v6, v6, v6
	v_min_f32_e32 v12, 0, v6
	s_waitcnt vmcnt(1)
	v_max_f32_e32 v11, v8, v8
	v_add_f32_e32 v13, 1.0, v10
	v_add_f32_e32 v14, -1.0, v13
	v_frexp_mant_f32_e32 v15, v13
	v_cvt_f64_f32_e32 v[6:7], v13
	v_sub_f32_e32 v16, v14, v13
	v_frexp_exp_i32_f64_e32 v6, v[6:7]
	v_cmp_gt_f32_e32 vcc, s33, v15
	v_sub_f32_e32 v14, v10, v14
	v_add_f32_e32 v7, 1.0, v16
	v_subbrev_co_u32_e32 v6, vcc, 0, v6, vcc
	v_add_f32_e32 v7, v14, v7
	v_sub_u32_e32 v14, 0, v6
	v_cvt_f32_i32_e32 v6, v6
	v_ldexp_f32 v13, v13, v14
	v_ldexp_f32 v7, v7, v14
	v_add_f32_e32 v14, -1.0, v13
	v_add_f32_e32 v15, 1.0, v13
	v_add_f32_e32 v16, 1.0, v14
	v_add_f32_e32 v17, -1.0, v15
	v_sub_f32_e32 v16, v13, v16
	v_sub_f32_e32 v13, v13, v17
	v_mul_f32_e32 v17, 0x3f317218, v6
	v_add_f32_e32 v16, v7, v16
	v_add_f32_e32 v7, v7, v13
	v_fma_f32 v13, v6, s34, -v17
	v_add_f32_e32 v18, v14, v16
	v_add_f32_e32 v20, v15, v7
	v_fmac_f32_e32 v13, 0xb102e308, v6
	v_sub_f32_e32 v6, v18, v14
	v_sub_f32_e32 v14, v20, v15
	v_rcp_f32_e32 v15, v20
	v_add_f32_e32 v21, v17, v13
	v_sub_f32_e32 v7, v7, v14
	v_sub_f32_e32 v14, v21, v17
	v_sub_f32_e32 v13, v13, v14
	v_mul_f32_e32 v14, v18, v15
	v_sub_f32_e32 v6, v16, v6
	v_mul_f32_e32 v16, v20, v14
	v_fma_f32 v17, v14, v20, -v16
	v_fmac_f32_e32 v17, v14, v7
	v_add_f32_e32 v22, v16, v17
	v_sub_f32_e32 v23, v18, v22
	v_sub_f32_e32 v16, v22, v16
	v_sub_f32_e32 v18, v18, v23
	v_sub_f32_e32 v16, v16, v17
	v_sub_f32_e32 v17, v18, v22
	v_add_f32_e32 v6, v6, v17
	v_add_f32_e32 v6, v16, v6
	v_add_f32_e32 v16, v23, v6
	v_mul_f32_e32 v17, v15, v16
	v_sub_f32_e32 v18, v23, v16
	v_mul_f32_e32 v22, v20, v17
	v_add_f32_e32 v6, v6, v18
	v_add_f32_e32 v18, v14, v17
	v_fma_f32 v20, v17, v20, -v22
	v_sub_f32_e32 v14, v18, v14
	v_fmac_f32_e32 v20, v17, v7
	v_sub_f32_e32 v7, v17, v14
	v_add_f32_e32 v14, v22, v20
	v_sub_f32_e32 v17, v14, v22
	v_sub_f32_e32 v22, v16, v14
	v_sub_f32_e32 v16, v16, v22
	v_sub_f32_e32 v14, v16, v14
	v_sub_f32_e32 v17, v17, v20
	v_add_f32_e32 v6, v6, v14
	v_add_f32_e32 v6, v17, v6
	v_add_f32_e32 v6, v22, v6
	v_mul_f32_e32 v6, v15, v6
	v_add_f32_e32 v6, v7, v6
	v_add_f32_e32 v7, v18, v6
	v_mul_f32_e32 v14, v7, v7
	v_fmamk_f32 v17, v14, 0x3e9b6dac, v138
	v_sub_f32_e32 v15, v7, v18
	v_ldexp_f32 v16, v7, 1
	v_mul_f32_e32 v7, v7, v14
	v_fmaak_f32 v14, v14, v17, 0x3f2aaada
	v_mul_f32_e32 v7, v7, v14
	v_add_f32_e32 v14, v16, v7
	v_sub_f32_e32 v6, v6, v15
	v_sub_f32_e32 v15, v14, v16
	v_ldexp_f32 v6, v6, 1
	v_sub_f32_e32 v7, v7, v15
	v_add_f32_e32 v6, v6, v7
	v_add_f32_e32 v7, v14, v6
	v_sub_f32_e32 v14, v7, v14
	v_add_f32_e32 v15, v21, v7
	v_sub_f32_e32 v6, v6, v14
	v_sub_f32_e32 v14, v15, v21
	v_sub_f32_e32 v16, v15, v14
	v_sub_f32_e32 v7, v7, v14
	v_add_f32_e32 v14, v13, v6
	v_sub_f32_e32 v16, v21, v16
	v_sub_f32_e32 v17, v14, v13
	v_add_f32_e32 v7, v7, v16
	v_sub_f32_e32 v16, v14, v17
	v_sub_f32_e32 v6, v6, v17
	v_sub_f32_e32 v13, v13, v16
	v_add_f32_e32 v7, v14, v7
	v_add_f32_e32 v6, v6, v13
	v_add_f32_e32 v13, v15, v7
	v_sub_f32_e32 v14, v13, v15
	v_sub_f32_e32 v7, v7, v14
	v_add_f32_e32 v6, v6, v7
	v_add_f32_e32 v6, v13, v6
	v_cmp_neq_f32_e32 vcc, s35, v10
	s_nop 1
	v_cndmask_b32_e32 v6, v181, v6, vcc
	v_cmp_ngt_f32_e32 vcc, -1.0, v10
	s_nop 1
	v_cndmask_b32_e32 v6, v182, v6, vcc
	v_cmp_neq_f32_e32 vcc, -1.0, v10
	s_nop 1
	v_cndmask_b32_e32 v6, v183, v6, vcc
	v_cmp_lt_f32_e64 vcc, |v10|, s36
	s_nop 1
	v_cndmask_b32_e32 v6, v6, v10, vcc
	v_sub_f32_e32 v6, v12, v6
	s_waitcnt vmcnt(0)
	v_add_f32_e32 v6, v9, v6
	v_max_f32_e32 v18, v6, v11
	v_sub_f32_e32 v6, v6, v18
	v_sub_f32_e32 v7, v8, v18
	v_mul_f32_e32 v28, 0x3fb8aa3b, v6
	v_add_co_u32_e32 v6, vcc, s37, v2
	v_mul_f32_e32 v29, 0x3fb8aa3b, v7
	s_nop 0
	v_addc_co_u32_e32 v7, vcc, 0, v3, vcc
	s_waitcnt vmcnt(0)
	v_mov_b32_e32 v49, v190
	v_mov_b32_e32 v50, v191
	v_mov_b32_e32 v51, v192
	v_mov_b32_e32 v52, v193
	v_mov_b32_e32 v53, v194
	v_mov_b32_e32 v54, v195
	v_mov_b32_e32 v55, v196
	v_mov_b32_e32 v16, v197
	v_mov_b32_e32 v17, v198
	v_mov_b32_e32 v14, v199
	v_mov_b32_e32 v15, v200
	v_add_co_u32_e32 v4, vcc, s22, v2
	s_nop 1
	v_addc_co_u32_e32 v5, vcc, 0, v3, vcc
	v_mov_b32_e32 v2, v201
	v_mov_b32_e32 v56, v202
	v_mov_b32_e32 v57, v203
	v_mov_b32_e32 v58, v204
	v_mov_b32_e32 v12, v205
	ds_read_b32 v3, v131 offset:1024
	ds_read_b128 v[20:23], v136
	v_mov_b32_e32 v13, v206
	v_mov_b32_e32 v10, v207
	v_mov_b32_e32 v11, v208
	v_mov_b32_e32 v8, v209
	v_mov_b32_e32 v9, v210
	v_mov_b32_e32 v6, v211
	v_mov_b32_e32 v7, v212
	ds_read_b128 v[24:27], v136 offset:512
	v_exp_f32_e32 v4, v29
	v_exp_f32_e32 v5, v28
	s_waitcnt vmcnt(31) lgkmcnt(1)
; DI void smlstm_unit(const Args& a, LAS unsigned char* lds, int s, int h) {
;     ...
;     float num = 0.f; float* Co = a.out + O_CS + (size_t)sh * 16384; const float vv = VF[dv];
;     { float c0v[32];
; #pragma unroll
;       for (int i = 0; i < 32; ++i) c0v[i] = C0[(size_t)(part * 32 + i) * 128 + dv];
; #pragma unroll
;       for (int i = 0; i < 32; ++i) { const int dk = part * 32 + i; num += QF[dk] * c0v[i]; Co[(size_t)dk * 128 + dv] = w_in * c0v[i] + wi * KF[dk] * vv; } }
;     RED[part * 128 + dv] = num;
;     __syncthreads();
	v_fma_f32 v59, v19, v20, 0
	s_waitcnt vmcnt(30)
	v_fmac_f32_e32 v59, v32, v21
	s_waitcnt lgkmcnt(0)
	v_mul_f32_e32 v20, v24, v4
	v_mul_f32_e32 v20, v3, v20
	v_fmac_f32_e32 v20, v19, v5
	v_mul_f32_e32 v19, v25, v4
	v_mul_f32_e32 v19, v3, v19
	v_fmac_f32_e32 v19, v32, v5
	global_store_dword v140, v19, s[20:21]
	v_mul_f32_e32 v19, v26, v4
	v_mul_f32_e32 v19, v3, v19
	s_waitcnt vmcnt(30)
	v_fmac_f32_e32 v19, v33, v5
	global_store_dword v141, v19, s[20:21]
	v_mul_f32_e32 v19, v27, v4
	v_mul_f32_e32 v19, v3, v19
	v_fmac_f32_e32 v59, v33, v22
	s_waitcnt vmcnt(30)
	v_fmac_f32_e32 v19, v34, v5
	ds_read_b128 v[28:31], v136 offset:112
	global_store_dword v139, v20, s[20:21]
	v_fmac_f32_e32 v59, v34, v23
	ds_read_b128 v[20:23], v136 offset:16
	global_store_dword v142, v19, s[20:21]
	ds_read_b128 v[24:27], v136 offset:528
	ds_read_b128 v[32:35], v136 offset:32
	ds_read_b128 v[36:39], v136 offset:48
	ds_read_b128 v[40:43], v136 offset:544
	s_waitcnt lgkmcnt(3)
	v_mul_f32_e32 v19, v24, v4
	s_waitcnt vmcnt(31)
	v_fmac_f32_e32 v59, v44, v20
	v_mul_f32_e32 v19, v3, v19
	v_fmac_f32_e32 v19, v44, v5
	s_waitcnt vmcnt(30)
	v_fmac_f32_e32 v59, v45, v21
	global_store_dword v143, v19, s[20:21]
	v_mul_f32_e32 v19, v25, v4
	s_waitcnt vmcnt(30)
	v_fmac_f32_e32 v59, v46, v22
	v_mul_f32_e32 v19, v3, v19
	s_waitcnt vmcnt(29)
	v_fmac_f32_e32 v59, v47, v23
	v_fmac_f32_e32 v19, v45, v5
	s_waitcnt vmcnt(28) lgkmcnt(2)
	v_fmac_f32_e32 v59, v48, v32
	global_store_dword v144, v19, s[20:21]
	v_mul_f32_e32 v19, v26, v4
	v_mul_f32_e32 v19, v3, v19
	v_fmac_f32_e32 v19, v46, v5
	global_store_dword v145, v19, s[20:21]
	v_mul_f32_e32 v19, v27, v4
	v_mul_f32_e32 v19, v3, v19
	v_fmac_f32_e32 v19, v47, v5
	global_store_dword v146, v19, s[20:21]
	ds_read_b128 v[20:23], v136 offset:560
	ds_read_b128 v[24:27], v136 offset:64
	s_waitcnt vmcnt(30)
	v_fmac_f32_e32 v59, v49, v33
	s_waitcnt vmcnt(29)
	v_fmac_f32_e32 v59, v50, v34
	s_waitcnt vmcnt(28)
	v_fmac_f32_e32 v59, v51, v35
	ds_read_b128 v[32:35], v136 offset:576
	s_waitcnt vmcnt(19) lgkmcnt(4)
	v_fmac_f32_e32 v59, v2, v36
	s_waitcnt vmcnt(18)
	v_fmac_f32_e32 v59, v56, v37
	s_waitcnt vmcnt(17)
	v_fmac_f32_e32 v59, v57, v38
	s_waitcnt vmcnt(16)
	v_fmac_f32_e32 v59, v58, v39
	ds_read_b128 v[36:39], v136 offset:96
	s_waitcnt lgkmcnt(4)
	v_mul_f32_e32 v19, v40, v4
	v_mul_f32_e32 v19, v3, v19
	v_fmac_f32_e32 v19, v48, v5
	global_store_dword v147, v19, s[20:21]
	v_mul_f32_e32 v19, v41, v4
	v_mul_f32_e32 v19, v3, v19
	v_fmac_f32_e32 v19, v49, v5
	global_store_dword v148, v19, s[20:21]
	v_mul_f32_e32 v19, v42, v4
	v_mul_f32_e32 v19, v3, v19
	v_fmac_f32_e32 v19, v50, v5
	global_store_dword v149, v19, s[20:21]
	v_mul_f32_e32 v19, v4, v43
	v_mul_f32_e32 v19, v3, v19
	v_fmac_f32_e32 v19, v51, v5
	global_store_dword v150, v19, s[20:21]
	s_waitcnt lgkmcnt(3)
	v_mul_f32_e32 v19, v4, v20
	v_mul_f32_e32 v19, v3, v19
	v_fmac_f32_e32 v19, v2, v5
	v_mul_f32_e32 v2, v4, v21
	v_mul_f32_e32 v2, v3, v2
	v_fmac_f32_e32 v2, v56, v5
	global_store_dword v152, v2, s[20:21]
	v_mul_f32_e32 v2, v4, v22
	v_mul_f32_e32 v2, v3, v2
	v_fmac_f32_e32 v2, v57, v5
	global_store_dword v153, v2, s[20:21]
	v_mul_f32_e32 v2, v4, v23
	v_mul_f32_e32 v2, v3, v2
	v_fmac_f32_e32 v2, v58, v5
	global_store_dword v154, v2, s[20:21]
	s_waitcnt lgkmcnt(1)
	v_mul_f32_e32 v2, v4, v32
	v_mul_f32_e32 v2, v3, v2
	v_fmac_f32_e32 v2, v52, v5
	global_store_dword v155, v2, s[20:21]
	v_mul_f32_e32 v2, v4, v33
	ds_read_b128 v[20:23], v136 offset:80
	v_fmac_f32_e32 v59, v52, v24
	v_mul_f32_e32 v2, v3, v2
	v_fmac_f32_e32 v59, v53, v25
	v_fmac_f32_e32 v2, v53, v5
	global_store_dword v156, v2, s[20:21]
	v_fmac_f32_e32 v59, v54, v26
	v_mul_f32_e32 v2, v4, v34
	v_mul_f32_e32 v2, v3, v2
	v_fmac_f32_e32 v59, v55, v27
	ds_read_b128 v[24:27], v136 offset:592
	v_fmac_f32_e32 v2, v54, v5
	global_store_dword v157, v2, s[20:21]
	v_mul_f32_e32 v2, v4, v35
	v_mul_f32_e32 v2, v3, v2
	v_fmac_f32_e32 v2, v55, v5
	global_store_dword v160, v2, s[20:21]
	ds_read_b128 v[32:35], v136 offset:608
	s_waitcnt lgkmcnt(1)
	v_mul_f32_e32 v2, v4, v24
	v_mul_f32_e32 v2, v3, v2
	v_fmac_f32_e32 v2, v16, v5
	v_pk_mul_f32 v[20:21], v[16:17], v[20:21]
	v_mul_f32_e32 v16, v4, v25
	v_mul_f32_e32 v16, v3, v16
	v_fmac_f32_e32 v16, v17, v5
	global_store_dword v162, v16, s[20:21]
	v_mul_f32_e32 v16, v4, v26
	v_mul_f32_e32 v16, v3, v16
	v_fmac_f32_e32 v16, v14, v5
	global_store_dword v163, v16, s[20:21]
	v_pk_mul_f32 v[16:17], v[14:15], v[22:23]
	v_mul_f32_e32 v14, v4, v27
	v_mul_f32_e32 v14, v3, v14
	v_fmac_f32_e32 v14, v15, v5
	global_store_dword v164, v14, s[20:21]
	s_waitcnt lgkmcnt(0)
	v_mul_f32_e32 v14, v4, v32
	v_mul_f32_e32 v14, v3, v14
	s_waitcnt vmcnt(29)
	v_fmac_f32_e32 v14, v12, v5
	global_store_dword v165, v14, s[20:21]
	s_waitcnt vmcnt(29)
	v_pk_mul_f32 v[14:15], v[12:13], v[36:37]
	v_mul_f32_e32 v12, v4, v33
	global_store_dword v161, v2, s[20:21]
	v_add_f32_e32 v2, v59, v20
	v_mul_f32_e32 v12, v3, v12
	v_add_f32_e32 v2, v2, v21
	v_fmac_f32_e32 v12, v13, v5
	v_add_f32_e32 v2, v2, v16
	global_store_dword v166, v12, s[20:21]
	v_mul_f32_e32 v12, v4, v34
	v_add_f32_e32 v2, v2, v17
	v_mul_f32_e32 v12, v3, v12
	v_add_f32_e32 v2, v2, v14
	s_waitcnt vmcnt(30)
	v_fmac_f32_e32 v12, v10, v5
	v_add_f32_e32 v2, v2, v15
	global_store_dword v167, v12, s[20:21]
	s_waitcnt vmcnt(30)
	v_pk_mul_f32 v[12:13], v[10:11], v[38:39]
	v_mul_f32_e32 v10, v4, v35
	v_add_f32_e32 v2, v2, v12
	v_add_f32_e32 v2, v2, v13
	ds_read_b128 v[12:15], v136 offset:624
	v_mul_f32_e32 v10, v3, v10
	v_fmac_f32_e32 v10, v11, v5
	global_store_dword v168, v10, s[20:21]
	global_store_dword v151, v19, s[20:21]
	s_waitcnt lgkmcnt(0)
	v_mul_f32_e32 v10, v4, v12
	v_mul_f32_e32 v10, v3, v10
	s_waitcnt vmcnt(31)
	v_fmac_f32_e32 v10, v8, v5
	global_store_dword v169, v10, s[20:21]
	s_waitcnt vmcnt(31)
	v_pk_mul_f32 v[10:11], v[8:9], v[28:29]
	v_mul_f32_e32 v8, v4, v13
	v_mul_f32_e32 v8, v3, v8
	v_fmac_f32_e32 v8, v9, v5
	global_store_dword v170, v8, s[20:21]
	v_mul_f32_e32 v8, v4, v14
	v_mul_f32_e32 v8, v3, v8
	v_add_f32_e32 v2, v2, v10
	s_waitcnt vmcnt(31)
	v_fmac_f32_e32 v8, v6, v5
	v_add_f32_e32 v2, v2, v11
	global_store_dword v171, v8, s[20:21]
	s_waitcnt vmcnt(31)
	v_pk_mul_f32 v[8:9], v[6:7], v[30:31]
	v_mul_f32_e32 v6, v4, v15
	v_add_f32_e32 v2, v2, v8
	v_mul_f32_e32 v6, v3, v6
	v_add_f32_e32 v2, v2, v9
	v_fmac_f32_e32 v6, v7, v5
	global_store_dword v172, v6, s[20:21]
	ds_write_b32 v218, v2 offset:1536
	s_waitcnt lgkmcnt(0)
	s_barrier
; DI void smlstm_unit(const Args& a, LAS unsigned char* lds, int s, int h) {
;     ...
;     if (tid < 128) { const float nt = (RED[dv] + RED[128 + dv]) + (RED[256 + dv] + RED[384 + dv]); const float sw = SCL[0] * wi; const float den = w_in * SCL[1] + sw;
;         HV[dv] = (w_in * nt + sw * vv) / fmaxf(fabsf(den), __expf(-mt));
;         a.out[O_NS + sh * 128 + dv] = w_in * n0[dv] + wi * KF[dv];
;         if (tid == 0) a.out[O_MS + sh] = mt; }
	s_and_saveexec_b64 s[20:21], s[2:3]
	s_cbranch_execz .LBB0_2134
	v_lshlrev_b32_e32 v132, 2, v130
	global_load_dword v6, v132, s[18:19]
	ds_read2st64_b32 v[8:9], v131 offset0:2 offset1:6
	ds_read2st64_b32 v[10:11], v218 offset0:8 offset1:10
	ds_read_b32 v13, v218 offset:3072
	ds_read_b64 v[14:15], v133 offset:4096
	v_mul_f32_e32 v7, 0xbfb8aa3b, v18
	s_waitcnt lgkmcnt(3)
	v_mov_b32_e32 v12, v9
	v_exp_f32_e32 v7, v7
	s_waitcnt lgkmcnt(1)
	v_pk_add_f32 v[10:11], v[10:11], v[12:13]
	v_mov_b32_e32 v2, v5
	v_mov_b32_e32 v16, v5
	v_mov_b32_e32 v17, v4
	s_waitcnt lgkmcnt(0)
	v_pk_mul_f32 v[4:5], v[4:5], v[14:15]
	v_pk_add_f32 v[10:11], v[10:11], v[10:11] op_sel:[0,1] op_sel_hi:[1,0]
	v_add_f32_e32 v5, v4, v5
	v_mov_b32_e32 v11, v4
	v_pk_mul_f32 v[2:3], v[2:3], v[10:11]
	v_max_f32_e64 v5, |v5|, v7
	v_add_f32_e32 v3, v2, v3
	v_div_scale_f32 v2, s[18:19], v5, v5, v3
	v_rcp_f32_e32 v4, v2
	v_mov_b32_e32 v7, v8
	v_div_scale_f32 v8, vcc, v3, v5, v3
	v_fma_f32 v9, -v2, v4, 1.0
	v_fmac_f32_e32 v4, v9, v4
	v_readlane_b32 s44, v253, 0
	v_mul_f32_e32 v9, v8, v4
	v_readlane_b32 s46, v253, 2
	v_fma_f32 v10, -v2, v9, v8
	v_readlane_b32 s47, v253, 3
	s_add_u32 s16, s46, s16
	v_fmac_f32_e32 v9, v10, v4
	s_addc_u32 s17, s47, s17
	v_fma_f32 v2, -v2, v9, v8
	v_lshl_add_u64 v[20:21], s[16:17], 0, v[132:133]
	v_div_fmas_f32 v4, v2, v4, v9
	v_add_co_u32_e32 v2, vcc, 0x7e34000, v20
	v_div_fixup_f32 v3, v4, v5, v3
	v_readlane_b32 s18, v254, 43
	ds_write_b32 v131, v3 offset:3584
	v_addc_co_u32_e32 v3, vcc, 0, v21, vcc
	v_readlane_b32 s19, v254, 44
	v_readlane_b32 s45, v253, 1
	s_waitcnt vmcnt(0)
	v_pk_mul_f32 v[4:5], v[16:17], v[6:7]
	s_nop 0
	v_add_f32_e32 v4, v4, v5
	global_store_dword v[2:3], v4, off offset:128
	s_and_b64 exec, exec, s[18:19]
	s_cbranch_execz .LBB0_2134
	s_mul_hi_i32 s9, s8, 0xfffffe04
	s_mulk_i32 s8, 0xfe04
	s_add_u32 s8, s16, s8
	s_addc_u32 s9, s17, s9
	global_store_dword v173, v18, s[8:9] offset:128
